# eight redundant lgkmcnt(0) after the phase barriers of the k-loop removed (the wait before each barrier already drains LDS)
# speedup vs baseline: 1.0054x; 1.0020x over previous
; #define PG8_STAGE(bufoff, gbase, voff) do { _Pragma("unroll") for (int _i = 0; _i < 2; ++_i) \
;         __builtin_amdgcn_global_load_lds((const unsigned*)((const char*)(gbase) + (voff)[_i]), (LAS unsigned*)(lds + (bufoff) + ldsw + _i * 8192), 16, 0, 0); } while (0)
; #define PG8_LDA(dst, b, h) do { _Pragma("unroll") for (int m = 0; m < 4; ++m) _Pragma("unroll") for (int k = 0; k < 2; ++k) dst[m][k] = *(const LAS bf16x8*)(lds + PG8_SA(b, h) + aoff + m * 2048 + k * 1024); } while (0)
; #define PG8_LDB(dst, b, h) do { _Pragma("unroll") for (int n = 0; n < 2; ++n) _Pragma("unroll") for (int k = 0; k < 2; ++k) dst[n][k] = *(const LAS bf16x8*)(lds + PG8_SB(b, h) + boff + n * 2048 + k * 1024); } while (0)
; #define PG8_MMA(ai, bj, At, Bt) do { __builtin_amdgcn_s_setprio(1); _Pragma("unroll") for (int m = 0; m < 4; ++m) _Pragma("unroll") for (int n = 0; n < 2; ++n) _Pragma("unroll") for (int k = 0; k < 2; ++k) \
;         acc[ai][bj][m][n] = __builtin_amdgcn_mfma_f32_16x16x32_bf16(Bt[n][k], At[m][k], acc[ai][bj][m][n], 0, 0, 0); __builtin_amdgcn_s_setprio(0); } while (0)
; #define PG8_WAIT_V(n) asm volatile("s_waitcnt vmcnt(" #n ")" ::: "memory")
; #define PG8_BAR __builtin_amdgcn_s_barrier()
; DI void gemm_phase(LAS unsigned char* lds, int ph, unsigned char* ws, unsigned char* wg, int l, const float* pscale, int G, int cidx, int nx) {
;     ...
;         for (int t = 0; t < nt; t += 2) {
;             const bool last = (t == nt - 2);
;             const char* a1 = PG8_KA(t + 1);
;             const char* a2 = last ? nA : PG8_KA(t + 2); const char* b2 = last ? nB : PG8_KB(t + 2);
;             const char* a3 = a2 + kstep; const char* b3 = b2 + kstep;
;             if (zAb != 0 && t != 0 && (t & ntzm) == 0) { unsigned char* wsx = ws; asm volatile("" : "+s"(wsx)); int frx = fr; asm volatile("" : "+v"(frx)); merge_carry(acc, wsx, cur, (t >> lz) - 1, wr, wc, frx, fq); }
;             PG8_LDB(B0, 0, 0); PG8_LDB(B1, 0, 1); PG8_SCHED; PG8_LDA(At, 0, 0); PG8_STAGE(PG8_SA(1, 1), a1 + hstepA, voffA);
;             PG8_WAIT_V(8); PG8_WAIT_L(0); PG8_BAR; PG8_MMA(0, 0, At, B0); PG8_MMA(0, 1, At, B1); PG8_BAR; PG8_SCHED;
;             PG8_LDA(At, 0, 1); PG8_STAGE(PG8_SB(0, 0), b2, voffB); PG8_STAGE(PG8_SB(0, 1), b2 + hstepB, voffB); PG8_STAGE(PG8_SA(0, 0), a2, voffA);
;             PG8_WAIT_V(8); PG8_WAIT_L(0); PG8_BAR; PG8_MMA(1, 0, At, B0); PG8_MMA(1, 1, At, B1); PG8_BAR; PG8_SCHED;
.Lpeel_501:
.Lpeel_500:
	v_add_u32_e32 v80, s91, v173
	s_add_i32 s20, 0, 0x14000
	ds_read_b128 v[132:135], v80
	ds_read_b128 v[136:139], v80 offset:1024
	ds_read_b128 v[142:145], v80 offset:2048
	ds_read_b128 v[158:161], v80 offset:3072
	v_add_u32_e32 v80, s20, v173
	ds_read_b128 v[176:179], v80
	ds_read_b128 v[180:183], v80 offset:1024
	ds_read_b128 v[184:187], v80 offset:2048
	ds_read_b128 v[188:191], v80 offset:3072
	ds_read_b128 v[192:195], v174
	ds_read_b128 v[196:199], v174 offset:1024
	ds_read_b128 v[200:203], v174 offset:2048
	ds_read_b128 v[204:207], v174 offset:3072
	ds_read_b128 v[208:211], v174 offset:4096
	ds_read_b128 v[212:215], v174 offset:5120
	ds_read_b128 v[216:219], v174 offset:6144
	ds_read_b128 v[220:223], v174 offset:7168
	s_add_i32 m0, s79, 0xc000
	s_add_i32 s12, s38, 1
	s_lshr_b32 s18, s12, s76
	s_mul_i32 s19, s53, s18
	s_mul_hi_u32 s21, s52, s18
	s_add_i32 s21, s21, s19
	s_mul_i32 s18, s52, s18
	s_add_u32 s18, s42, s18
	s_addc_u32 s19, s43, s21
	s_and_b32 s12, s12, s83
	s_lshl_b32 s12, s12, 7
	s_add_u32 s12, s18, s12
	s_addc_u32 s19, s19, 0
	s_add_u32 s18, s12, s7
	s_addc_u32 s19, s19, 0
	global_load_lds_dwordx4 v150, s[18:19]
	s_add_i32 m0, s79, 0xe000
	s_nop 0
	global_load_lds_dwordx4 v154, s[18:19]
	s_waitcnt vmcnt(8)
	s_waitcnt lgkmcnt(0)
	s_barrier
	s_setprio 1
	v_mfma_f32_16x16x32_bf16 v[128:131], v[132:135], v[192:195], 0
	s_add_i32 s0, s38, 2
	v_mfma_f32_16x16x32_bf16 v[124:127], v[142:145], v[192:195], 0
	s_lshr_b32 s1, s0, s76
	v_mfma_f32_16x16x32_bf16 v[112:115], v[132:135], v[200:203], 0
	s_mul_i32 s12, s53, s1
	v_mfma_f32_16x16x32_bf16 v[108:111], v[142:145], v[200:203], 0
	s_mul_hi_u32 s18, s52, s1
	v_mfma_f32_16x16x32_bf16 v[96:99], v[132:135], v[208:211], 0
	s_add_i32 s18, s18, s12
	v_mfma_f32_16x16x32_bf16 v[92:95], v[142:145], v[208:211], 0
	s_mul_i32 s12, s52, s1
	v_mfma_f32_16x16x32_bf16 v[76:79], v[132:135], v[216:219], 0
	s_and_b32 s0, s0, s83
	v_mfma_f32_16x16x32_bf16 v[72:75], v[142:145], v[216:219], 0
	s_lshl_b32 s0, s0, 7
	v_mfma_f32_16x16x32_bf16 v[128:131], v[136:139], v[196:199], v[128:131]
	s_mul_i32 s19, s49, s1
	v_mfma_f32_16x16x32_bf16 v[124:127], v[158:161], v[196:199], v[124:127]
	s_mul_hi_u32 s21, s48, s1
	v_mfma_f32_16x16x32_bf16 v[112:115], v[136:139], v[204:207], v[112:115]
	s_add_i32 s21, s21, s19
	v_mfma_f32_16x16x32_bf16 v[108:111], v[158:161], v[204:207], v[108:111]
	s_mul_i32 s19, s48, s1
	v_mfma_f32_16x16x32_bf16 v[96:99], v[136:139], v[212:215], v[96:99]
	s_add_u32 s12, s42, s12
	v_mfma_f32_16x16x32_bf16 v[92:95], v[158:161], v[212:215], v[92:95]
	s_addc_u32 s18, s43, s18
	v_mfma_f32_16x16x32_bf16 v[76:79], v[136:139], v[220:223], v[76:79]
	s_add_u32 s12, s12, s0
	v_mfma_f32_16x16x32_bf16 v[72:75], v[158:161], v[220:223], v[72:75]
	s_addc_u32 s18, s18, 0
	v_mfma_f32_16x16x32_bf16 v[120:123], v[176:179], v[192:195], 0
	s_add_u32 s19, s40, s19
	v_mfma_f32_16x16x32_bf16 v[116:119], v[184:187], v[192:195], 0
	s_addc_u32 s21, s41, s21
	v_mfma_f32_16x16x32_bf16 v[104:107], v[176:179], v[200:203], 0
	s_add_u32 s19, s19, s0
	v_mfma_f32_16x16x32_bf16 v[100:103], v[184:187], v[200:203], 0
	s_addc_u32 s21, s21, 0
	v_mfma_f32_16x16x32_bf16 v[88:91], v[176:179], v[208:211], 0
	s_cmp_eq_u32 s96, s38
	v_mfma_f32_16x16x32_bf16 v[82:85], v[184:187], v[208:211], 0
	s_cselect_b32 s0, s60, s12
	v_mfma_f32_16x16x32_bf16 v[68:71], v[176:179], v[216:219], 0
	s_cselect_b32 s1, s61, s18
	v_mfma_f32_16x16x32_bf16 v[64:67], v[184:187], v[216:219], 0
	s_cselect_b32 s64, s62, s19
	v_mfma_f32_16x16x32_bf16 v[120:123], v[180:183], v[196:199], v[120:123]
	s_cselect_b32 s65, s63, s21
	v_mfma_f32_16x16x32_bf16 v[116:119], v[188:191], v[196:199], v[116:119]
	v_mfma_f32_16x16x32_bf16 v[104:107], v[180:183], v[204:207], v[104:107]
	v_mfma_f32_16x16x32_bf16 v[100:103], v[188:191], v[204:207], v[100:103]
	v_mfma_f32_16x16x32_bf16 v[88:91], v[180:183], v[212:215], v[88:91]
	v_mfma_f32_16x16x32_bf16 v[82:85], v[188:191], v[212:215], v[82:85]
	v_mfma_f32_16x16x32_bf16 v[68:71], v[180:183], v[220:223], v[68:71]
	v_mfma_f32_16x16x32_bf16 v[64:67], v[188:191], v[220:223], v[64:67]
	s_setprio 0
	s_barrier
	s_add_i32 s12, s91, s78
	s_mov_b32 m0, s12
	ds_read_b128 v[192:195], v174 offset:16384
	ds_read_b128 v[196:199], v174 offset:17408
	ds_read_b128 v[200:203], v174 offset:18432
	ds_read_b128 v[204:207], v174 offset:19456
	ds_read_b128 v[208:211], v174 offset:20480
	ds_read_b128 v[212:215], v174 offset:21504
	ds_read_b128 v[216:219], v174 offset:22528
	ds_read_b128 v[220:223], v174 offset:23552
	global_load_lds_dwordx4 v152, s[64:65]
	s_add_i32 m0, s12, 0x2000
	s_add_u32 s18, s64, s77
	s_addc_u32 s19, s65, 0
	s_add_i32 s12, s20, s78
	global_load_lds_dwordx4 v156, s[64:65]
	s_mov_b32 m0, s12
	s_nop 0
	global_load_lds_dwordx4 v152, s[18:19]
	s_add_i32 m0, s12, 0x2000
	s_nop 0
	global_load_lds_dwordx4 v156, s[18:19]
	s_mov_b32 m0, s79
	s_nop 0
	global_load_lds_dwordx4 v150, s[0:1]
	s_mov_b32 m0, s80
	s_nop 0
	global_load_lds_dwordx4 v154, s[0:1]
	s_waitcnt vmcnt(8)
	s_waitcnt lgkmcnt(0)
	s_barrier
; #define PG8_STAGE(bufoff, gbase, voff) do { _Pragma("unroll") for (int _i = 0; _i < 2; ++_i) \
;         __builtin_amdgcn_global_load_lds((const unsigned*)((const char*)(gbase) + (voff)[_i]), (LAS unsigned*)(lds + (bufoff) + ldsw + _i * 8192), 16, 0, 0); } while (0)
; #define PG8_LDA(dst, b, h) do { _Pragma("unroll") for (int m = 0; m < 4; ++m) _Pragma("unroll") for (int k = 0; k < 2; ++k) dst[m][k] = *(const LAS bf16x8*)(lds + PG8_SA(b, h) + aoff + m * 2048 + k * 1024); } while (0)
; #define PG8_LDB(dst, b, h) do { _Pragma("unroll") for (int n = 0; n < 2; ++n) _Pragma("unroll") for (int k = 0; k < 2; ++k) dst[n][k] = *(const LAS bf16x8*)(lds + PG8_SB(b, h) + boff + n * 2048 + k * 1024); } while (0)
; #define PG8_MMA(ai, bj, At, Bt) do { __builtin_amdgcn_s_setprio(1); _Pragma("unroll") for (int m = 0; m < 4; ++m) _Pragma("unroll") for (int n = 0; n < 2; ++n) _Pragma("unroll") for (int k = 0; k < 2; ++k) \
;         acc[ai][bj][m][n] = __builtin_amdgcn_mfma_f32_16x16x32_bf16(Bt[n][k], At[m][k], acc[ai][bj][m][n], 0, 0, 0); __builtin_amdgcn_s_setprio(0); } while (0)
; #define PG8_WAIT_V(n) asm volatile("s_waitcnt vmcnt(" #n ")" ::: "memory")
; #define PG8_WAIT_L(n) asm volatile("s_waitcnt lgkmcnt(" #n ")" ::: "memory")
; #define PG8_BAR __builtin_amdgcn_s_barrier()
; #define PG8_SCHED __builtin_amdgcn_sched_barrier(0)
; DI void gemm_phase(LAS unsigned char* lds, int ph, unsigned char* ws, unsigned char* wg, int l, const float* pscale, int G, int cidx, int nx) {
;     ...
;             PG8_WAIT_V(8); PG8_WAIT_L(0); PG8_BAR; PG8_MMA(1, 0, At, B0); PG8_MMA(1, 1, At, B1); PG8_BAR; PG8_SCHED;
;             PG8_LDB(B0, 1, 0); PG8_LDB(B1, 1, 1); PG8_SCHED; PG8_LDA(At, 1, 0); PG8_STAGE(PG8_SA(0, 1), a2 + hstepA, voffA);
;             PG8_WAIT_V(8); PG8_WAIT_L(0); PG8_BAR; PG8_MMA(0, 0, At, B0); PG8_MMA(0, 1, At, B1); PG8_BAR; PG8_SCHED;
	s_setprio 1
	v_mfma_f32_16x16x32_bf16 v[60:63], v[132:135], v[192:195], 0
	v_mfma_f32_16x16x32_bf16 v[56:59], v[142:145], v[192:195], 0
	v_mfma_f32_16x16x32_bf16 v[44:47], v[132:135], v[200:203], 0
	v_mfma_f32_16x16x32_bf16 v[40:43], v[142:145], v[200:203], 0
	v_mfma_f32_16x16x32_bf16 v[28:31], v[132:135], v[208:211], 0
	v_mfma_f32_16x16x32_bf16 v[24:27], v[142:145], v[208:211], 0
	v_mfma_f32_16x16x32_bf16 v[12:15], v[132:135], v[216:219], 0
	v_mfma_f32_16x16x32_bf16 v[8:11], v[142:145], v[216:219], 0
	v_mfma_f32_16x16x32_bf16 v[60:63], v[136:139], v[196:199], v[60:63]
	v_mfma_f32_16x16x32_bf16 v[56:59], v[158:161], v[196:199], v[56:59]
	v_mfma_f32_16x16x32_bf16 v[44:47], v[136:139], v[204:207], v[44:47]
	v_mfma_f32_16x16x32_bf16 v[40:43], v[158:161], v[204:207], v[40:43]
	v_mfma_f32_16x16x32_bf16 v[28:31], v[136:139], v[212:215], v[28:31]
	v_mfma_f32_16x16x32_bf16 v[24:27], v[158:161], v[212:215], v[24:27]
	v_mfma_f32_16x16x32_bf16 v[12:15], v[136:139], v[220:223], v[12:15]
	v_mfma_f32_16x16x32_bf16 v[8:11], v[158:161], v[220:223], v[8:11]
	v_mfma_f32_16x16x32_bf16 v[52:55], v[176:179], v[192:195], 0
	v_mfma_f32_16x16x32_bf16 v[48:51], v[184:187], v[192:195], 0
	v_mfma_f32_16x16x32_bf16 v[36:39], v[176:179], v[200:203], 0
	v_mfma_f32_16x16x32_bf16 v[32:35], v[184:187], v[200:203], 0
	v_mfma_f32_16x16x32_bf16 v[20:23], v[176:179], v[208:211], 0
	v_mfma_f32_16x16x32_bf16 v[16:19], v[184:187], v[208:211], 0
	v_mfma_f32_16x16x32_bf16 v[4:7], v[176:179], v[216:219], 0
	v_mfma_f32_16x16x32_bf16 v[0:3], v[184:187], v[216:219], 0
	v_mfma_f32_16x16x32_bf16 v[52:55], v[180:183], v[196:199], v[52:55]
	v_mfma_f32_16x16x32_bf16 v[48:51], v[188:191], v[196:199], v[48:51]
	v_mfma_f32_16x16x32_bf16 v[36:39], v[180:183], v[204:207], v[36:39]
	v_mfma_f32_16x16x32_bf16 v[32:35], v[188:191], v[204:207], v[32:35]
	v_mfma_f32_16x16x32_bf16 v[20:23], v[180:183], v[212:215], v[20:23]
	v_mfma_f32_16x16x32_bf16 v[16:19], v[188:191], v[212:215], v[16:19]
	v_mfma_f32_16x16x32_bf16 v[4:7], v[180:183], v[220:223], v[4:7]
	v_mfma_f32_16x16x32_bf16 v[0:3], v[188:191], v[220:223], v[0:3]
	s_setprio 0
	s_barrier
	s_add_i32 s12, 0, 0x18000
	v_add_u32_e32 v80, s12, v173
	s_add_i32 s18, 0, 0x1c000
	ds_read_b128 v[132:135], v80
	ds_read_b128 v[136:139], v80 offset:1024
	ds_read_b128 v[142:145], v80 offset:2048
	ds_read_b128 v[158:161], v80 offset:3072
	v_add_u32_e32 v80, s18, v173
	ds_read_b128 v[176:179], v80
	ds_read_b128 v[180:183], v80 offset:1024
	ds_read_b128 v[184:187], v80 offset:2048
	ds_read_b128 v[188:191], v80 offset:3072
	s_add_u32 s0, s0, s7
	s_addc_u32 s1, s1, 0
	s_mov_b32 m0, s81
	ds_read_b128 v[192:195], v174 offset:32768
	ds_read_b128 v[196:199], v174 offset:33792
	ds_read_b128 v[200:203], v174 offset:34816
	ds_read_b128 v[204:207], v174 offset:35840
	ds_read_b128 v[208:211], v174 offset:36864
	ds_read_b128 v[212:215], v174 offset:37888
	ds_read_b128 v[216:219], v174 offset:38912
	ds_read_b128 v[220:223], v174 offset:39936
	global_load_lds_dwordx4 v150, s[0:1]
	s_mov_b32 m0, s82
	s_nop 0
	global_load_lds_dwordx4 v154, s[0:1]
	s_waitcnt vmcnt(8)
	s_waitcnt lgkmcnt(0)
	s_barrier
	s_setprio 1
	v_mfma_f32_16x16x32_bf16 v[128:131], v[132:135], v[192:195], v[128:131]
	s_sub_u32 s20, s0, s7
	v_mfma_f32_16x16x32_bf16 v[124:127], v[142:145], v[192:195], v[124:127]
	s_subb_u32 s21, s1, 0
	v_mfma_f32_16x16x32_bf16 v[112:115], v[132:135], v[200:203], v[112:115]
	s_add_u32 s20, s20, s4
	v_mfma_f32_16x16x32_bf16 v[108:111], v[142:145], v[200:203], v[108:111]
	s_addc_u32 s21, s21, s5
	v_mfma_f32_16x16x32_bf16 v[96:99], v[132:135], v[208:211], v[96:99]
	s_add_u32 s0, s64, s4
	v_mfma_f32_16x16x32_bf16 v[92:95], v[142:145], v[208:211], v[92:95]
	s_addc_u32 s1, s65, s5
	v_mfma_f32_16x16x32_bf16 v[76:79], v[132:135], v[216:219], v[76:79]
	v_mfma_f32_16x16x32_bf16 v[72:75], v[142:145], v[216:219], v[72:75]
	v_mfma_f32_16x16x32_bf16 v[128:131], v[136:139], v[196:199], v[128:131]
	v_mfma_f32_16x16x32_bf16 v[124:127], v[158:161], v[196:199], v[124:127]
	v_mfma_f32_16x16x32_bf16 v[112:115], v[136:139], v[204:207], v[112:115]
	v_mfma_f32_16x16x32_bf16 v[108:111], v[158:161], v[204:207], v[108:111]
	v_mfma_f32_16x16x32_bf16 v[96:99], v[136:139], v[212:215], v[96:99]
	v_mfma_f32_16x16x32_bf16 v[92:95], v[158:161], v[212:215], v[92:95]
	v_mfma_f32_16x16x32_bf16 v[76:79], v[136:139], v[220:223], v[76:79]
	v_mfma_f32_16x16x32_bf16 v[72:75], v[158:161], v[220:223], v[72:75]
	v_mfma_f32_16x16x32_bf16 v[120:123], v[176:179], v[192:195], v[120:123]
	v_mfma_f32_16x16x32_bf16 v[116:119], v[184:187], v[192:195], v[116:119]
	v_mfma_f32_16x16x32_bf16 v[104:107], v[176:179], v[200:203], v[104:107]
	v_mfma_f32_16x16x32_bf16 v[100:103], v[184:187], v[200:203], v[100:103]
	v_mfma_f32_16x16x32_bf16 v[86:89], v[176:179], v[208:211], v[88:91]
	v_mfma_f32_16x16x32_bf16 v[82:85], v[184:187], v[208:211], v[82:85]
	v_mfma_f32_16x16x32_bf16 v[68:71], v[176:179], v[216:219], v[68:71]
	v_mfma_f32_16x16x32_bf16 v[64:67], v[184:187], v[216:219], v[64:67]
	v_mfma_f32_16x16x32_bf16 v[120:123], v[180:183], v[196:199], v[120:123]
	v_mfma_f32_16x16x32_bf16 v[116:119], v[188:191], v[196:199], v[116:119]
	v_mfma_f32_16x16x32_bf16 v[104:107], v[180:183], v[204:207], v[104:107]
	v_mfma_f32_16x16x32_bf16 v[100:103], v[188:191], v[204:207], v[100:103]
	v_mfma_f32_16x16x32_bf16 v[88:91], v[180:183], v[212:215], v[86:89]
	v_mfma_f32_16x16x32_bf16 v[84:87], v[188:191], v[212:215], v[82:85]
	v_mfma_f32_16x16x32_bf16 v[68:71], v[180:183], v[220:223], v[68:71]
	v_mfma_f32_16x16x32_bf16 v[64:67], v[188:191], v[220:223], v[64:67]
	s_setprio 0
	s_barrier
; #define PG8_STAGE(bufoff, gbase, voff) do { _Pragma("unroll") for (int _i = 0; _i < 2; ++_i) \
;         __builtin_amdgcn_global_load_lds((const unsigned*)((const char*)(gbase) + (voff)[_i]), (LAS unsigned*)(lds + (bufoff) + ldsw + _i * 8192), 16, 0, 0); } while (0)
; #define PG8_LDA(dst, b, h) do { _Pragma("unroll") for (int m = 0; m < 4; ++m) _Pragma("unroll") for (int k = 0; k < 2; ++k) dst[m][k] = *(const LAS bf16x8*)(lds + PG8_SA(b, h) + aoff + m * 2048 + k * 1024); } while (0)
; #define PG8_LDB(dst, b, h) do { _Pragma("unroll") for (int n = 0; n < 2; ++n) _Pragma("unroll") for (int k = 0; k < 2; ++k) dst[n][k] = *(const LAS bf16x8*)(lds + PG8_SB(b, h) + boff + n * 2048 + k * 1024); } while (0)
; #define PG8_MMA(ai, bj, At, Bt) do { __builtin_amdgcn_s_setprio(1); _Pragma("unroll") for (int m = 0; m < 4; ++m) _Pragma("unroll") for (int n = 0; n < 2; ++n) _Pragma("unroll") for (int k = 0; k < 2; ++k) \
;         acc[ai][bj][m][n] = __builtin_amdgcn_mfma_f32_16x16x32_bf16(Bt[n][k], At[m][k], acc[ai][bj][m][n], 0, 0, 0); __builtin_amdgcn_s_setprio(0); } while (0)
; #define PG8_WAIT_V(n) asm volatile("s_waitcnt vmcnt(" #n ")" ::: "memory")
; #define PG8_BAR __builtin_amdgcn_s_barrier()
; DI void gemm_phase(LAS unsigned char* lds, int ph, unsigned char* ws, unsigned char* wg, int l, const float* pscale, int G, int cidx, int nx) {
;     ...
;         for (int t = 0; t < nt; t += 2) {
;             const bool last = (t == nt - 2);
;             const char* a1 = PG8_KA(t + 1);
;             const char* a2 = last ? nA : PG8_KA(t + 2); const char* b2 = last ? nB : PG8_KB(t + 2);
;             const char* a3 = a2 + kstep; const char* b3 = b2 + kstep;
;             if (zAb != 0 && t != 0 && (t & ntzm) == 0) { unsigned char* wsx = ws; asm volatile("" : "+s"(wsx)); int frx = fr; asm volatile("" : "+v"(frx)); merge_carry(acc, wsx, cur, (t >> lz) - 1, wr, wc, frx, fq); }
;             PG8_LDB(B0, 0, 0); PG8_LDB(B1, 0, 1); PG8_SCHED; PG8_LDA(At, 0, 0); PG8_STAGE(PG8_SA(1, 1), a1 + hstepA, voffA);
;             PG8_WAIT_V(8); PG8_WAIT_L(0); PG8_BAR; PG8_MMA(0, 0, At, B0); PG8_MMA(0, 1, At, B1); PG8_BAR; PG8_SCHED;
;     ...
;             PG8_LDA(At, 1, 1); PG8_STAGE(PG8_SB(1, 0), b3, voffB); PG8_STAGE(PG8_SB(1, 1), b3 + hstepB, voffB); PG8_STAGE(PG8_SA(1, 0), a3, voffA);
;             PG8_WAIT_V(8); PG8_WAIT_L(0); PG8_BAR; PG8_MMA(1, 0, At, B0); PG8_MMA(1, 1, At, B1); PG8_BAR; PG8_SCHED;
	s_add_i32 s19, s12, s78
	s_mov_b32 m0, s19
	ds_read_b128 v[192:195], v174 offset:49152
	ds_read_b128 v[196:199], v174 offset:50176
	ds_read_b128 v[200:203], v174 offset:51200
	ds_read_b128 v[204:207], v174 offset:52224
	ds_read_b128 v[208:211], v174 offset:53248
	ds_read_b128 v[212:215], v174 offset:54272
	ds_read_b128 v[216:219], v174 offset:55296
	ds_read_b128 v[220:223], v174 offset:56320
	global_load_lds_dwordx4 v152, s[0:1]
	s_add_i32 m0, s19, 0x2000
	s_add_i32 s19, s18, s78
	global_load_lds_dwordx4 v156, s[0:1]
	s_add_u32 s0, s0, s77
	s_addc_u32 s1, s1, 0
	s_mov_b32 m0, s19
	s_nop 0
	global_load_lds_dwordx4 v152, s[0:1]
	s_add_i32 m0, s19, 0x2000
	s_nop 0
	global_load_lds_dwordx4 v156, s[0:1]
	s_mov_b32 m0, s93
	s_nop 0
	global_load_lds_dwordx4 v150, s[20:21]
	s_mov_b32 m0, s94
	s_nop 0
	global_load_lds_dwordx4 v154, s[20:21]
	s_waitcnt vmcnt(8)
	s_waitcnt lgkmcnt(0)
	s_barrier
	s_setprio 1
	v_mfma_f32_16x16x32_bf16 v[60:63], v[132:135], v[192:195], v[60:63]
	s_add_i32 s38, s38, 2
	v_mfma_f32_16x16x32_bf16 v[56:59], v[142:145], v[192:195], v[56:59]
	s_cmp_ge_u32 s38, s75
	v_mfma_f32_16x16x32_bf16 v[44:47], v[132:135], v[200:203], v[44:47]
	v_mfma_f32_16x16x32_bf16 v[40:43], v[142:145], v[200:203], v[40:43]
	v_mfma_f32_16x16x32_bf16 v[28:31], v[132:135], v[208:211], v[28:31]
	v_mfma_f32_16x16x32_bf16 v[24:27], v[142:145], v[208:211], v[24:27]
	v_mfma_f32_16x16x32_bf16 v[12:15], v[132:135], v[216:219], v[12:15]
	v_mfma_f32_16x16x32_bf16 v[8:11], v[142:145], v[216:219], v[8:11]
	v_mfma_f32_16x16x32_bf16 v[60:63], v[136:139], v[196:199], v[60:63]
	v_mfma_f32_16x16x32_bf16 v[56:59], v[158:161], v[196:199], v[56:59]
	v_mfma_f32_16x16x32_bf16 v[44:47], v[136:139], v[204:207], v[44:47]
	v_mfma_f32_16x16x32_bf16 v[40:43], v[158:161], v[204:207], v[40:43]
	v_mfma_f32_16x16x32_bf16 v[28:31], v[136:139], v[212:215], v[28:31]
	v_mfma_f32_16x16x32_bf16 v[24:27], v[158:161], v[212:215], v[24:27]
	v_mfma_f32_16x16x32_bf16 v[12:15], v[136:139], v[220:223], v[12:15]
	v_mfma_f32_16x16x32_bf16 v[8:11], v[158:161], v[220:223], v[8:11]
	v_mfma_f32_16x16x32_bf16 v[52:55], v[176:179], v[192:195], v[52:55]
	v_mfma_f32_16x16x32_bf16 v[48:51], v[184:187], v[192:195], v[48:51]
	v_mfma_f32_16x16x32_bf16 v[36:39], v[176:179], v[200:203], v[36:39]
	v_mfma_f32_16x16x32_bf16 v[32:35], v[184:187], v[200:203], v[32:35]
	v_mfma_f32_16x16x32_bf16 v[20:23], v[176:179], v[208:211], v[20:23]
	v_mfma_f32_16x16x32_bf16 v[16:19], v[184:187], v[208:211], v[16:19]
	v_mfma_f32_16x16x32_bf16 v[4:7], v[176:179], v[216:219], v[4:7]
	v_mfma_f32_16x16x32_bf16 v[0:3], v[184:187], v[216:219], v[0:3]
	v_mfma_f32_16x16x32_bf16 v[52:55], v[180:183], v[196:199], v[52:55]
	v_mfma_f32_16x16x32_bf16 v[48:51], v[188:191], v[196:199], v[48:51]
	v_mfma_f32_16x16x32_bf16 v[36:39], v[180:183], v[204:207], v[36:39]
	v_mfma_f32_16x16x32_bf16 v[32:35], v[188:191], v[204:207], v[32:35]
	v_mfma_f32_16x16x32_bf16 v[20:23], v[180:183], v[212:215], v[20:23]
	v_mfma_f32_16x16x32_bf16 v[16:19], v[188:191], v[212:215], v[16:19]
	v_mfma_f32_16x16x32_bf16 v[4:7], v[180:183], v[220:223], v[4:7]
	v_mfma_f32_16x16x32_bf16 v[0:3], v[188:191], v[220:223], v[0:3]
	s_setprio 0
	s_barrier
	s_cbranch_scc1 .LBB0_507
	s_branch .LBB0_501
.LBB0_500:
	v_add_u32_e32 v80, s91, v173
	s_add_i32 s20, 0, 0x14000
	ds_read_b128 v[132:135], v80
	ds_read_b128 v[136:139], v80 offset:1024
	ds_read_b128 v[142:145], v80 offset:2048
	ds_read_b128 v[158:161], v80 offset:3072
	v_add_u32_e32 v80, s20, v173
	ds_read_b128 v[176:179], v80
	ds_read_b128 v[180:183], v80 offset:1024
	ds_read_b128 v[184:187], v80 offset:2048
	ds_read_b128 v[188:191], v80 offset:3072
	ds_read_b128 v[192:195], v174
	ds_read_b128 v[196:199], v174 offset:1024
	ds_read_b128 v[200:203], v174 offset:2048
	ds_read_b128 v[204:207], v174 offset:3072
	ds_read_b128 v[208:211], v174 offset:4096
	ds_read_b128 v[212:215], v174 offset:5120
	ds_read_b128 v[216:219], v174 offset:6144
	ds_read_b128 v[220:223], v174 offset:7168
	s_add_i32 m0, s79, 0xc000
	s_add_i32 s12, s38, 1
	s_lshr_b32 s18, s12, s76
	s_mul_i32 s19, s53, s18
	s_mul_hi_u32 s21, s52, s18
	s_add_i32 s21, s21, s19
	s_mul_i32 s18, s52, s18
	s_add_u32 s18, s42, s18
	s_addc_u32 s19, s43, s21
	s_and_b32 s12, s12, s83
	s_lshl_b32 s12, s12, 7
	s_add_u32 s12, s18, s12
	s_addc_u32 s19, s19, 0
	s_add_u32 s18, s12, s7
	s_addc_u32 s19, s19, 0
	global_load_lds_dwordx4 v150, s[18:19]
	s_add_i32 m0, s79, 0xe000
	s_nop 0
	global_load_lds_dwordx4 v154, s[18:19]
	s_waitcnt vmcnt(8)
	s_waitcnt lgkmcnt(0)
	s_barrier
; #define PG8_STAGE(bufoff, gbase, voff) do { _Pragma("unroll") for (int _i = 0; _i < 2; ++_i) \
;         __builtin_amdgcn_global_load_lds((const unsigned*)((const char*)(gbase) + (voff)[_i]), (LAS unsigned*)(lds + (bufoff) + ldsw + _i * 8192), 16, 0, 0); } while (0)
; #define PG8_LDA(dst, b, h) do { _Pragma("unroll") for (int m = 0; m < 4; ++m) _Pragma("unroll") for (int k = 0; k < 2; ++k) dst[m][k] = *(const LAS bf16x8*)(lds + PG8_SA(b, h) + aoff + m * 2048 + k * 1024); } while (0)
; #define PG8_LDB(dst, b, h) do { _Pragma("unroll") for (int n = 0; n < 2; ++n) _Pragma("unroll") for (int k = 0; k < 2; ++k) dst[n][k] = *(const LAS bf16x8*)(lds + PG8_SB(b, h) + boff + n * 2048 + k * 1024); } while (0)
; #define PG8_MMA(ai, bj, At, Bt) do { __builtin_amdgcn_s_setprio(1); _Pragma("unroll") for (int m = 0; m < 4; ++m) _Pragma("unroll") for (int n = 0; n < 2; ++n) _Pragma("unroll") for (int k = 0; k < 2; ++k) \
;         acc[ai][bj][m][n] = __builtin_amdgcn_mfma_f32_16x16x32_bf16(Bt[n][k], At[m][k], acc[ai][bj][m][n], 0, 0, 0); __builtin_amdgcn_s_setprio(0); } while (0)
; #define PG8_WAIT_V(n) asm volatile("s_waitcnt vmcnt(" #n ")" ::: "memory")
; #define PG8_WAIT_L(n) asm volatile("s_waitcnt lgkmcnt(" #n ")" ::: "memory")
; #define PG8_BAR __builtin_amdgcn_s_barrier()
; #define PG8_SCHED __builtin_amdgcn_sched_barrier(0)
; DI void gemm_phase(LAS unsigned char* lds, int ph, unsigned char* ws, unsigned char* wg, int l, const float* pscale, int G, int cidx, int nx) {
;     ...
;             PG8_WAIT_V(8); PG8_WAIT_L(0); PG8_BAR; PG8_MMA(0, 0, At, B0); PG8_MMA(0, 1, At, B1); PG8_BAR; PG8_SCHED;
;             PG8_LDA(At, 0, 1); PG8_STAGE(PG8_SB(0, 0), b2, voffB); PG8_STAGE(PG8_SB(0, 1), b2 + hstepB, voffB); PG8_STAGE(PG8_SA(0, 0), a2, voffA);
;             PG8_WAIT_V(8); PG8_WAIT_L(0); PG8_BAR; PG8_MMA(1, 0, At, B0); PG8_MMA(1, 1, At, B1); PG8_BAR; PG8_SCHED;
;             PG8_LDB(B0, 1, 0); PG8_LDB(B1, 1, 1); PG8_SCHED; PG8_LDA(At, 1, 0); PG8_STAGE(PG8_SA(0, 1), a2 + hstepA, voffA);
;             PG8_WAIT_V(8); PG8_WAIT_L(0); PG8_BAR; PG8_MMA(0, 0, At, B0); PG8_MMA(0, 1, At, B1); PG8_BAR; PG8_SCHED;
	s_setprio 1
	v_mfma_f32_16x16x32_bf16 v[128:131], v[132:135], v[192:195], v[128:131]
	s_add_i32 s0, s38, 2
	v_mfma_f32_16x16x32_bf16 v[124:127], v[142:145], v[192:195], v[124:127]
	s_lshr_b32 s1, s0, s76
	v_mfma_f32_16x16x32_bf16 v[112:115], v[132:135], v[200:203], v[112:115]
	s_mul_i32 s12, s53, s1
	v_mfma_f32_16x16x32_bf16 v[108:111], v[142:145], v[200:203], v[108:111]
	s_mul_hi_u32 s18, s52, s1
	v_mfma_f32_16x16x32_bf16 v[96:99], v[132:135], v[208:211], v[96:99]
	s_add_i32 s18, s18, s12
	v_mfma_f32_16x16x32_bf16 v[92:95], v[142:145], v[208:211], v[92:95]
	s_mul_i32 s12, s52, s1
	v_mfma_f32_16x16x32_bf16 v[76:79], v[132:135], v[216:219], v[76:79]
	s_and_b32 s0, s0, s83
	v_mfma_f32_16x16x32_bf16 v[72:75], v[142:145], v[216:219], v[72:75]
	s_lshl_b32 s0, s0, 7
	v_mfma_f32_16x16x32_bf16 v[128:131], v[136:139], v[196:199], v[128:131]
	s_mul_i32 s19, s49, s1
	v_mfma_f32_16x16x32_bf16 v[124:127], v[158:161], v[196:199], v[124:127]
	s_mul_hi_u32 s21, s48, s1
	v_mfma_f32_16x16x32_bf16 v[112:115], v[136:139], v[204:207], v[112:115]
	s_add_i32 s21, s21, s19
	v_mfma_f32_16x16x32_bf16 v[108:111], v[158:161], v[204:207], v[108:111]
	s_mul_i32 s19, s48, s1
	v_mfma_f32_16x16x32_bf16 v[96:99], v[136:139], v[212:215], v[96:99]
	s_add_u32 s12, s42, s12
	v_mfma_f32_16x16x32_bf16 v[92:95], v[158:161], v[212:215], v[92:95]
	s_addc_u32 s18, s43, s18
	v_mfma_f32_16x16x32_bf16 v[76:79], v[136:139], v[220:223], v[76:79]
	s_add_u32 s12, s12, s0
	v_mfma_f32_16x16x32_bf16 v[72:75], v[158:161], v[220:223], v[72:75]
	s_addc_u32 s18, s18, 0
	v_mfma_f32_16x16x32_bf16 v[120:123], v[176:179], v[192:195], v[120:123]
	s_add_u32 s19, s40, s19
	v_mfma_f32_16x16x32_bf16 v[116:119], v[184:187], v[192:195], v[116:119]
	s_addc_u32 s21, s41, s21
	v_mfma_f32_16x16x32_bf16 v[104:107], v[176:179], v[200:203], v[104:107]
	s_add_u32 s19, s19, s0
	v_mfma_f32_16x16x32_bf16 v[100:103], v[184:187], v[200:203], v[100:103]
	s_addc_u32 s21, s21, 0
	v_mfma_f32_16x16x32_bf16 v[88:91], v[176:179], v[208:211], v[88:91]
	s_cmp_eq_u32 s96, s38
	v_mfma_f32_16x16x32_bf16 v[82:85], v[184:187], v[208:211], v[84:87]
	s_cselect_b32 s0, s60, s12
	v_mfma_f32_16x16x32_bf16 v[68:71], v[176:179], v[216:219], v[68:71]
	s_cselect_b32 s1, s61, s18
	v_mfma_f32_16x16x32_bf16 v[64:67], v[184:187], v[216:219], v[64:67]
	s_cselect_b32 s64, s62, s19
	v_mfma_f32_16x16x32_bf16 v[120:123], v[180:183], v[196:199], v[120:123]
	s_cselect_b32 s65, s63, s21
	v_mfma_f32_16x16x32_bf16 v[116:119], v[188:191], v[196:199], v[116:119]
	v_mfma_f32_16x16x32_bf16 v[104:107], v[180:183], v[204:207], v[104:107]
	v_mfma_f32_16x16x32_bf16 v[100:103], v[188:191], v[204:207], v[100:103]
	v_mfma_f32_16x16x32_bf16 v[88:91], v[180:183], v[212:215], v[88:91]
	v_mfma_f32_16x16x32_bf16 v[82:85], v[188:191], v[212:215], v[82:85]
	v_mfma_f32_16x16x32_bf16 v[68:71], v[180:183], v[220:223], v[68:71]
	v_mfma_f32_16x16x32_bf16 v[64:67], v[188:191], v[220:223], v[64:67]
	s_setprio 0
	s_barrier
	s_add_i32 s12, s91, s78
	s_mov_b32 m0, s12
	ds_read_b128 v[192:195], v174 offset:16384
	ds_read_b128 v[196:199], v174 offset:17408
	ds_read_b128 v[200:203], v174 offset:18432
	ds_read_b128 v[204:207], v174 offset:19456
	ds_read_b128 v[208:211], v174 offset:20480
	ds_read_b128 v[212:215], v174 offset:21504
	ds_read_b128 v[216:219], v174 offset:22528
	ds_read_b128 v[220:223], v174 offset:23552
	global_load_lds_dwordx4 v152, s[64:65]
	s_add_i32 m0, s12, 0x2000
	s_add_u32 s18, s64, s77
	s_addc_u32 s19, s65, 0
	s_add_i32 s12, s20, s78
	global_load_lds_dwordx4 v156, s[64:65]
	s_mov_b32 m0, s12
	s_nop 0
	global_load_lds_dwordx4 v152, s[18:19]
	s_add_i32 m0, s12, 0x2000
	s_nop 0
	global_load_lds_dwordx4 v156, s[18:19]
	s_mov_b32 m0, s79
	s_nop 0
	global_load_lds_dwordx4 v150, s[0:1]
	s_mov_b32 m0, s80
	s_nop 0
	global_load_lds_dwordx4 v154, s[0:1]
	s_waitcnt vmcnt(8)
	s_waitcnt lgkmcnt(0)
	s_barrier
	s_setprio 1
	v_mfma_f32_16x16x32_bf16 v[60:63], v[132:135], v[192:195], v[60:63]
	v_mfma_f32_16x16x32_bf16 v[56:59], v[142:145], v[192:195], v[56:59]
	v_mfma_f32_16x16x32_bf16 v[44:47], v[132:135], v[200:203], v[44:47]
	v_mfma_f32_16x16x32_bf16 v[40:43], v[142:145], v[200:203], v[40:43]
	v_mfma_f32_16x16x32_bf16 v[28:31], v[132:135], v[208:211], v[28:31]
	v_mfma_f32_16x16x32_bf16 v[24:27], v[142:145], v[208:211], v[24:27]
	v_mfma_f32_16x16x32_bf16 v[12:15], v[132:135], v[216:219], v[12:15]
	v_mfma_f32_16x16x32_bf16 v[8:11], v[142:145], v[216:219], v[8:11]
	v_mfma_f32_16x16x32_bf16 v[60:63], v[136:139], v[196:199], v[60:63]
	v_mfma_f32_16x16x32_bf16 v[56:59], v[158:161], v[196:199], v[56:59]
	v_mfma_f32_16x16x32_bf16 v[44:47], v[136:139], v[204:207], v[44:47]
	v_mfma_f32_16x16x32_bf16 v[40:43], v[158:161], v[204:207], v[40:43]
	v_mfma_f32_16x16x32_bf16 v[28:31], v[136:139], v[212:215], v[28:31]
	v_mfma_f32_16x16x32_bf16 v[24:27], v[158:161], v[212:215], v[24:27]
	v_mfma_f32_16x16x32_bf16 v[12:15], v[136:139], v[220:223], v[12:15]
	v_mfma_f32_16x16x32_bf16 v[8:11], v[158:161], v[220:223], v[8:11]
	v_mfma_f32_16x16x32_bf16 v[52:55], v[176:179], v[192:195], v[52:55]
	v_mfma_f32_16x16x32_bf16 v[48:51], v[184:187], v[192:195], v[48:51]
	v_mfma_f32_16x16x32_bf16 v[36:39], v[176:179], v[200:203], v[36:39]
	v_mfma_f32_16x16x32_bf16 v[32:35], v[184:187], v[200:203], v[32:35]
	v_mfma_f32_16x16x32_bf16 v[20:23], v[176:179], v[208:211], v[20:23]
	v_mfma_f32_16x16x32_bf16 v[16:19], v[184:187], v[208:211], v[16:19]
	v_mfma_f32_16x16x32_bf16 v[4:7], v[176:179], v[216:219], v[4:7]
	v_mfma_f32_16x16x32_bf16 v[0:3], v[184:187], v[216:219], v[0:3]
	v_mfma_f32_16x16x32_bf16 v[52:55], v[180:183], v[196:199], v[52:55]
	v_mfma_f32_16x16x32_bf16 v[48:51], v[188:191], v[196:199], v[48:51]
	v_mfma_f32_16x16x32_bf16 v[36:39], v[180:183], v[204:207], v[36:39]
	v_mfma_f32_16x16x32_bf16 v[32:35], v[188:191], v[204:207], v[32:35]
	v_mfma_f32_16x16x32_bf16 v[20:23], v[180:183], v[212:215], v[20:23]
	v_mfma_f32_16x16x32_bf16 v[16:19], v[188:191], v[212:215], v[16:19]
	v_mfma_f32_16x16x32_bf16 v[4:7], v[180:183], v[220:223], v[4:7]
	v_mfma_f32_16x16x32_bf16 v[0:3], v[188:191], v[220:223], v[0:3]
	s_setprio 0
	s_barrier
; #define PG8_STAGE(bufoff, gbase, voff) do { _Pragma("unroll") for (int _i = 0; _i < 2; ++_i) \
;         __builtin_amdgcn_global_load_lds((const unsigned*)((const char*)(gbase) + (voff)[_i]), (LAS unsigned*)(lds + (bufoff) + ldsw + _i * 8192), 16, 0, 0); } while (0)
; #define PG8_LDA(dst, b, h) do { _Pragma("unroll") for (int m = 0; m < 4; ++m) _Pragma("unroll") for (int k = 0; k < 2; ++k) dst[m][k] = *(const LAS bf16x8*)(lds + PG8_SA(b, h) + aoff + m * 2048 + k * 1024); } while (0)
; #define PG8_LDB(dst, b, h) do { _Pragma("unroll") for (int n = 0; n < 2; ++n) _Pragma("unroll") for (int k = 0; k < 2; ++k) dst[n][k] = *(const LAS bf16x8*)(lds + PG8_SB(b, h) + boff + n * 2048 + k * 1024); } while (0)
; #define PG8_MMA(ai, bj, At, Bt) do { __builtin_amdgcn_s_setprio(1); _Pragma("unroll") for (int m = 0; m < 4; ++m) _Pragma("unroll") for (int n = 0; n < 2; ++n) _Pragma("unroll") for (int k = 0; k < 2; ++k) \
;         acc[ai][bj][m][n] = __builtin_amdgcn_mfma_f32_16x16x32_bf16(Bt[n][k], At[m][k], acc[ai][bj][m][n], 0, 0, 0); __builtin_amdgcn_s_setprio(0); } while (0)
; #define PG8_WAIT_V(n) asm volatile("s_waitcnt vmcnt(" #n ")" ::: "memory")
; #define PG8_WAIT_L(n) asm volatile("s_waitcnt lgkmcnt(" #n ")" ::: "memory")
; #define PG8_BAR __builtin_amdgcn_s_barrier()
; #define PG8_SCHED __builtin_amdgcn_sched_barrier(0)
; DI void gemm_phase(LAS unsigned char* lds, int ph, unsigned char* ws, unsigned char* wg, int l, const float* pscale, int G, int cidx, int nx) {
;     ...
;             PG8_LDB(B0, 1, 0); PG8_LDB(B1, 1, 1); PG8_SCHED; PG8_LDA(At, 1, 0); PG8_STAGE(PG8_SA(0, 1), a2 + hstepA, voffA);
;             PG8_WAIT_V(8); PG8_WAIT_L(0); PG8_BAR; PG8_MMA(0, 0, At, B0); PG8_MMA(0, 1, At, B1); PG8_BAR; PG8_SCHED;
;             PG8_LDA(At, 1, 1); PG8_STAGE(PG8_SB(1, 0), b3, voffB); PG8_STAGE(PG8_SB(1, 1), b3 + hstepB, voffB); PG8_STAGE(PG8_SA(1, 0), a3, voffA);
;             PG8_WAIT_V(8); PG8_WAIT_L(0); PG8_BAR; PG8_MMA(1, 0, At, B0); PG8_MMA(1, 1, At, B1); PG8_BAR; PG8_SCHED;
	s_add_i32 s12, 0, 0x18000
	v_add_u32_e32 v80, s12, v173
	s_add_i32 s18, 0, 0x1c000
	ds_read_b128 v[132:135], v80
	ds_read_b128 v[136:139], v80 offset:1024
	ds_read_b128 v[142:145], v80 offset:2048
	ds_read_b128 v[158:161], v80 offset:3072
	v_add_u32_e32 v80, s18, v173
	ds_read_b128 v[176:179], v80
	ds_read_b128 v[180:183], v80 offset:1024
	ds_read_b128 v[184:187], v80 offset:2048
	ds_read_b128 v[188:191], v80 offset:3072
	s_add_u32 s0, s0, s7
	s_addc_u32 s1, s1, 0
	s_mov_b32 m0, s81
	ds_read_b128 v[192:195], v174 offset:32768
	ds_read_b128 v[196:199], v174 offset:33792
	ds_read_b128 v[200:203], v174 offset:34816
	ds_read_b128 v[204:207], v174 offset:35840
	ds_read_b128 v[208:211], v174 offset:36864
	ds_read_b128 v[212:215], v174 offset:37888
	ds_read_b128 v[216:219], v174 offset:38912
	ds_read_b128 v[220:223], v174 offset:39936
	global_load_lds_dwordx4 v150, s[0:1]
	s_mov_b32 m0, s82
	s_nop 0
	global_load_lds_dwordx4 v154, s[0:1]
	s_waitcnt vmcnt(8)
	s_waitcnt lgkmcnt(0)
	s_barrier
	s_setprio 1
	v_mfma_f32_16x16x32_bf16 v[128:131], v[132:135], v[192:195], v[128:131]
	s_sub_u32 s20, s0, s7
	v_mfma_f32_16x16x32_bf16 v[124:127], v[142:145], v[192:195], v[124:127]
	s_subb_u32 s21, s1, 0
	v_mfma_f32_16x16x32_bf16 v[112:115], v[132:135], v[200:203], v[112:115]
	s_add_u32 s20, s20, s4
	v_mfma_f32_16x16x32_bf16 v[108:111], v[142:145], v[200:203], v[108:111]
	s_addc_u32 s21, s21, s5
	v_mfma_f32_16x16x32_bf16 v[96:99], v[132:135], v[208:211], v[96:99]
	s_add_u32 s0, s64, s4
	v_mfma_f32_16x16x32_bf16 v[92:95], v[142:145], v[208:211], v[92:95]
	s_addc_u32 s1, s65, s5
	v_mfma_f32_16x16x32_bf16 v[76:79], v[132:135], v[216:219], v[76:79]
	v_mfma_f32_16x16x32_bf16 v[72:75], v[142:145], v[216:219], v[72:75]
	v_mfma_f32_16x16x32_bf16 v[128:131], v[136:139], v[196:199], v[128:131]
	v_mfma_f32_16x16x32_bf16 v[124:127], v[158:161], v[196:199], v[124:127]
	v_mfma_f32_16x16x32_bf16 v[112:115], v[136:139], v[204:207], v[112:115]
	v_mfma_f32_16x16x32_bf16 v[108:111], v[158:161], v[204:207], v[108:111]
	v_mfma_f32_16x16x32_bf16 v[96:99], v[136:139], v[212:215], v[96:99]
	v_mfma_f32_16x16x32_bf16 v[92:95], v[158:161], v[212:215], v[92:95]
	v_mfma_f32_16x16x32_bf16 v[76:79], v[136:139], v[220:223], v[76:79]
	v_mfma_f32_16x16x32_bf16 v[72:75], v[158:161], v[220:223], v[72:75]
	v_mfma_f32_16x16x32_bf16 v[120:123], v[176:179], v[192:195], v[120:123]
	v_mfma_f32_16x16x32_bf16 v[116:119], v[184:187], v[192:195], v[116:119]
	v_mfma_f32_16x16x32_bf16 v[104:107], v[176:179], v[200:203], v[104:107]
	v_mfma_f32_16x16x32_bf16 v[100:103], v[184:187], v[200:203], v[100:103]
	v_mfma_f32_16x16x32_bf16 v[86:89], v[176:179], v[208:211], v[88:91]
	v_mfma_f32_16x16x32_bf16 v[82:85], v[184:187], v[208:211], v[82:85]
	v_mfma_f32_16x16x32_bf16 v[68:71], v[176:179], v[216:219], v[68:71]
	v_mfma_f32_16x16x32_bf16 v[64:67], v[184:187], v[216:219], v[64:67]
	v_mfma_f32_16x16x32_bf16 v[120:123], v[180:183], v[196:199], v[120:123]
	v_mfma_f32_16x16x32_bf16 v[116:119], v[188:191], v[196:199], v[116:119]
	v_mfma_f32_16x16x32_bf16 v[104:107], v[180:183], v[204:207], v[104:107]
	v_mfma_f32_16x16x32_bf16 v[100:103], v[188:191], v[204:207], v[100:103]
	v_mfma_f32_16x16x32_bf16 v[88:91], v[180:183], v[212:215], v[86:89]
	v_mfma_f32_16x16x32_bf16 v[84:87], v[188:191], v[212:215], v[82:85]
	v_mfma_f32_16x16x32_bf16 v[68:71], v[180:183], v[220:223], v[68:71]
	v_mfma_f32_16x16x32_bf16 v[64:67], v[188:191], v[220:223], v[64:67]
	s_setprio 0
	s_barrier
	s_add_i32 s19, s12, s78
	s_mov_b32 m0, s19
	ds_read_b128 v[192:195], v174 offset:49152
	ds_read_b128 v[196:199], v174 offset:50176
	ds_read_b128 v[200:203], v174 offset:51200
	ds_read_b128 v[204:207], v174 offset:52224
	ds_read_b128 v[208:211], v174 offset:53248
	ds_read_b128 v[212:215], v174 offset:54272
	ds_read_b128 v[216:219], v174 offset:55296
	ds_read_b128 v[220:223], v174 offset:56320
	global_load_lds_dwordx4 v152, s[0:1]
	s_add_i32 m0, s19, 0x2000
	s_add_i32 s19, s18, s78
	global_load_lds_dwordx4 v156, s[0:1]
	s_add_u32 s0, s0, s77
	s_addc_u32 s1, s1, 0
	s_mov_b32 m0, s19
	s_nop 0
	global_load_lds_dwordx4 v152, s[0:1]
	s_add_i32 m0, s19, 0x2000
	s_nop 0
	global_load_lds_dwordx4 v156, s[0:1]
	s_mov_b32 m0, s93
	s_nop 0
	global_load_lds_dwordx4 v150, s[20:21]
	s_mov_b32 m0, s94
	s_nop 0
	global_load_lds_dwordx4 v154, s[20:21]
	s_waitcnt vmcnt(8)
	s_waitcnt lgkmcnt(0)
	s_barrier
	s_setprio 1
	v_mfma_f32_16x16x32_bf16 v[60:63], v[132:135], v[192:195], v[60:63]
	s_add_i32 s38, s38, 2
	v_mfma_f32_16x16x32_bf16 v[56:59], v[142:145], v[192:195], v[56:59]
	s_cmp_ge_u32 s38, s75
	v_mfma_f32_16x16x32_bf16 v[44:47], v[132:135], v[200:203], v[44:47]
	v_mfma_f32_16x16x32_bf16 v[40:43], v[142:145], v[200:203], v[40:43]
	v_mfma_f32_16x16x32_bf16 v[28:31], v[132:135], v[208:211], v[28:31]
	v_mfma_f32_16x16x32_bf16 v[24:27], v[142:145], v[208:211], v[24:27]
	v_mfma_f32_16x16x32_bf16 v[12:15], v[132:135], v[216:219], v[12:15]
	v_mfma_f32_16x16x32_bf16 v[8:11], v[142:145], v[216:219], v[8:11]
	v_mfma_f32_16x16x32_bf16 v[60:63], v[136:139], v[196:199], v[60:63]
	v_mfma_f32_16x16x32_bf16 v[56:59], v[158:161], v[196:199], v[56:59]
	v_mfma_f32_16x16x32_bf16 v[44:47], v[136:139], v[204:207], v[44:47]
	v_mfma_f32_16x16x32_bf16 v[40:43], v[158:161], v[204:207], v[40:43]
	v_mfma_f32_16x16x32_bf16 v[28:31], v[136:139], v[212:215], v[28:31]
	v_mfma_f32_16x16x32_bf16 v[24:27], v[158:161], v[212:215], v[24:27]
	v_mfma_f32_16x16x32_bf16 v[12:15], v[136:139], v[220:223], v[12:15]
	v_mfma_f32_16x16x32_bf16 v[8:11], v[158:161], v[220:223], v[8:11]
	v_mfma_f32_16x16x32_bf16 v[52:55], v[176:179], v[192:195], v[52:55]
	v_mfma_f32_16x16x32_bf16 v[48:51], v[184:187], v[192:195], v[48:51]
	v_mfma_f32_16x16x32_bf16 v[36:39], v[176:179], v[200:203], v[36:39]
	v_mfma_f32_16x16x32_bf16 v[32:35], v[184:187], v[200:203], v[32:35]
	v_mfma_f32_16x16x32_bf16 v[20:23], v[176:179], v[208:211], v[20:23]
	v_mfma_f32_16x16x32_bf16 v[16:19], v[184:187], v[208:211], v[16:19]
	v_mfma_f32_16x16x32_bf16 v[4:7], v[176:179], v[216:219], v[4:7]
	v_mfma_f32_16x16x32_bf16 v[0:3], v[184:187], v[216:219], v[0:3]
	v_mfma_f32_16x16x32_bf16 v[52:55], v[180:183], v[196:199], v[52:55]
	v_mfma_f32_16x16x32_bf16 v[48:51], v[188:191], v[196:199], v[48:51]
	v_mfma_f32_16x16x32_bf16 v[36:39], v[180:183], v[204:207], v[36:39]
	v_mfma_f32_16x16x32_bf16 v[32:35], v[188:191], v[204:207], v[32:35]
	v_mfma_f32_16x16x32_bf16 v[20:23], v[180:183], v[212:215], v[20:23]
	v_mfma_f32_16x16x32_bf16 v[16:19], v[188:191], v[212:215], v[16:19]
	v_mfma_f32_16x16x32_bf16 v[4:7], v[180:183], v[220:223], v[4:7]
	v_mfma_f32_16x16x32_bf16 v[0:3], v[188:191], v[220:223], v[0:3]
	s_setprio 0
	s_barrier
	s_cbranch_scc1 .LBB0_507
